# P2 gate epilogue: in-place f32 sigmoid via v_exp+v_rcp instead of IEEE div sequence, reuses identity staging
# speedup vs baseline: 1.0533x; 1.0109x over previous
; DI float sigmoidf_(float x) { return 1.f / (1.f + __expf(-x)); }
; DI void phase2(const Params& p, char* smem) {
;     ...
;     if (ft >= 5) stage_half<4, 2, 4, 0>(acc, tile, 528, [](float v) { return sigmoidf_(v); });
;     else stage_half<4, 2, 4, 0>(acc, tile, 528, [](float v) { return v; });
.LBB0_278:
	s_cmp_lt_i32 s36, 5
	s_cselect_b64 s[10:11], -1, 0
	s_mov_b64 s[4:5], -1
	s_and_b64 vcc, exec, s[10:11]
	s_cbranch_vccnz .Lp2_id0
	v_mul_f32_e32 v64, 0xbfb8aa3b, v64
	v_mul_f32_e32 v65, 0xbfb8aa3b, v65
	v_mul_f32_e32 v66, 0xbfb8aa3b, v66
	v_mul_f32_e32 v67, 0xbfb8aa3b, v67
	v_mul_f32_e32 v68, 0xbfb8aa3b, v68
	v_mul_f32_e32 v69, 0xbfb8aa3b, v69
	v_mul_f32_e32 v70, 0xbfb8aa3b, v70
	v_mul_f32_e32 v71, 0xbfb8aa3b, v71
	v_exp_f32_e32 v64, v64
	v_exp_f32_e32 v65, v65
	v_exp_f32_e32 v66, v66
	v_exp_f32_e32 v67, v67
	v_exp_f32_e32 v68, v68
	v_exp_f32_e32 v69, v69
	v_exp_f32_e32 v70, v70
	v_exp_f32_e32 v71, v71
	v_add_f32_e32 v64, 1.0, v64
	v_add_f32_e32 v65, 1.0, v65
	v_add_f32_e32 v66, 1.0, v66
	v_add_f32_e32 v67, 1.0, v67
	v_add_f32_e32 v68, 1.0, v68
	v_add_f32_e32 v69, 1.0, v69
	v_add_f32_e32 v70, 1.0, v70
	v_add_f32_e32 v71, 1.0, v71
	v_rcp_f32_e32 v64, v64
	v_rcp_f32_e32 v65, v65
	v_rcp_f32_e32 v66, v66
	v_rcp_f32_e32 v67, v67
	v_rcp_f32_e32 v68, v68
	v_rcp_f32_e32 v69, v69
	v_rcp_f32_e32 v70, v70
	v_rcp_f32_e32 v71, v71
	v_mul_f32_e32 v72, 0xbfb8aa3b, v72
	v_mul_f32_e32 v73, 0xbfb8aa3b, v73
	v_mul_f32_e32 v74, 0xbfb8aa3b, v74
	v_mul_f32_e32 v75, 0xbfb8aa3b, v75
	v_mul_f32_e32 v76, 0xbfb8aa3b, v76
	v_mul_f32_e32 v77, 0xbfb8aa3b, v77
	v_mul_f32_e32 v78, 0xbfb8aa3b, v78
	v_mul_f32_e32 v79, 0xbfb8aa3b, v79
	v_exp_f32_e32 v72, v72
	v_exp_f32_e32 v73, v73
	v_exp_f32_e32 v74, v74
	v_exp_f32_e32 v75, v75
	v_exp_f32_e32 v76, v76
	v_exp_f32_e32 v77, v77
	v_exp_f32_e32 v78, v78
	v_exp_f32_e32 v79, v79
	v_add_f32_e32 v72, 1.0, v72
	v_add_f32_e32 v73, 1.0, v73
	v_add_f32_e32 v74, 1.0, v74
	v_add_f32_e32 v75, 1.0, v75
	v_add_f32_e32 v76, 1.0, v76
	v_add_f32_e32 v77, 1.0, v77
	v_add_f32_e32 v78, 1.0, v78
	v_add_f32_e32 v79, 1.0, v79
	v_rcp_f32_e32 v72, v72
	v_rcp_f32_e32 v73, v73
	v_rcp_f32_e32 v74, v74
	v_rcp_f32_e32 v75, v75
	v_rcp_f32_e32 v76, v76
	v_rcp_f32_e32 v77, v77
	v_rcp_f32_e32 v78, v78
	v_rcp_f32_e32 v79, v79
	v_mul_f32_e32 v80, 0xbfb8aa3b, v80
	v_mul_f32_e32 v81, 0xbfb8aa3b, v81
	v_mul_f32_e32 v82, 0xbfb8aa3b, v82
	v_mul_f32_e32 v83, 0xbfb8aa3b, v83
	v_mul_f32_e32 v84, 0xbfb8aa3b, v84
	v_mul_f32_e32 v85, 0xbfb8aa3b, v85
	v_mul_f32_e32 v86, 0xbfb8aa3b, v86
	v_mul_f32_e32 v87, 0xbfb8aa3b, v87
	v_exp_f32_e32 v80, v80
	v_exp_f32_e32 v81, v81
	v_exp_f32_e32 v82, v82
	v_exp_f32_e32 v83, v83
	v_exp_f32_e32 v84, v84
	v_exp_f32_e32 v85, v85
	v_exp_f32_e32 v86, v86
	v_exp_f32_e32 v87, v87
	v_add_f32_e32 v80, 1.0, v80
	v_add_f32_e32 v81, 1.0, v81
	v_add_f32_e32 v82, 1.0, v82
	v_add_f32_e32 v83, 1.0, v83
	v_add_f32_e32 v84, 1.0, v84
	v_add_f32_e32 v85, 1.0, v85
	v_add_f32_e32 v86, 1.0, v86
	v_add_f32_e32 v87, 1.0, v87
	v_rcp_f32_e32 v80, v80
	v_rcp_f32_e32 v81, v81
	v_rcp_f32_e32 v82, v82
	v_rcp_f32_e32 v83, v83
	v_rcp_f32_e32 v84, v84
	v_rcp_f32_e32 v85, v85
	v_rcp_f32_e32 v86, v86
	v_rcp_f32_e32 v87, v87
	v_mul_f32_e32 v88, 0xbfb8aa3b, v88
	v_mul_f32_e32 v89, 0xbfb8aa3b, v89
	v_mul_f32_e32 v90, 0xbfb8aa3b, v90
	v_mul_f32_e32 v91, 0xbfb8aa3b, v91
	v_mul_f32_e32 v92, 0xbfb8aa3b, v92
	v_mul_f32_e32 v93, 0xbfb8aa3b, v93
	v_mul_f32_e32 v94, 0xbfb8aa3b, v94
	v_mul_f32_e32 v95, 0xbfb8aa3b, v95
	v_exp_f32_e32 v88, v88
	v_exp_f32_e32 v89, v89
	v_exp_f32_e32 v90, v90
	v_exp_f32_e32 v91, v91
	v_exp_f32_e32 v92, v92
	v_exp_f32_e32 v93, v93
	v_exp_f32_e32 v94, v94
	v_exp_f32_e32 v95, v95
	v_add_f32_e32 v88, 1.0, v88
	v_add_f32_e32 v89, 1.0, v89
	v_add_f32_e32 v90, 1.0, v90
	v_add_f32_e32 v91, 1.0, v91
	v_add_f32_e32 v92, 1.0, v92
	v_add_f32_e32 v93, 1.0, v93
	v_add_f32_e32 v94, 1.0, v94
	v_add_f32_e32 v95, 1.0, v95
	v_rcp_f32_e32 v88, v88
	v_rcp_f32_e32 v89, v89
	v_rcp_f32_e32 v90, v90
	v_rcp_f32_e32 v91, v91
	v_rcp_f32_e32 v92, v92
	v_rcp_f32_e32 v93, v93
	v_rcp_f32_e32 v94, v94
	v_rcp_f32_e32 v95, v95
	v_mul_f32_e32 v96, 0xbfb8aa3b, v96
	v_mul_f32_e32 v97, 0xbfb8aa3b, v97
	v_mul_f32_e32 v98, 0xbfb8aa3b, v98
	v_mul_f32_e32 v99, 0xbfb8aa3b, v99
	v_mul_f32_e32 v100, 0xbfb8aa3b, v100
	v_mul_f32_e32 v101, 0xbfb8aa3b, v101
	v_mul_f32_e32 v102, 0xbfb8aa3b, v102
	v_mul_f32_e32 v103, 0xbfb8aa3b, v103
	v_exp_f32_e32 v96, v96
	v_exp_f32_e32 v97, v97
	v_exp_f32_e32 v98, v98
	v_exp_f32_e32 v99, v99
	v_exp_f32_e32 v100, v100
	v_exp_f32_e32 v101, v101
	v_exp_f32_e32 v102, v102
	v_exp_f32_e32 v103, v103
	v_add_f32_e32 v96, 1.0, v96
	v_add_f32_e32 v97, 1.0, v97
	v_add_f32_e32 v98, 1.0, v98
	v_add_f32_e32 v99, 1.0, v99
	v_add_f32_e32 v100, 1.0, v100
	v_add_f32_e32 v101, 1.0, v101
	v_add_f32_e32 v102, 1.0, v102
	v_add_f32_e32 v103, 1.0, v103
	v_rcp_f32_e32 v96, v96
	v_rcp_f32_e32 v97, v97
	v_rcp_f32_e32 v98, v98
	v_rcp_f32_e32 v99, v99
	v_rcp_f32_e32 v100, v100
	v_rcp_f32_e32 v101, v101
	v_rcp_f32_e32 v102, v102
	v_rcp_f32_e32 v103, v103
	v_mul_f32_e32 v104, 0xbfb8aa3b, v104
	v_mul_f32_e32 v105, 0xbfb8aa3b, v105
	v_mul_f32_e32 v106, 0xbfb8aa3b, v106
	v_mul_f32_e32 v107, 0xbfb8aa3b, v107
; DI unsigned pk_bf16(float lo, float hi) { f32x2v v = {lo, hi}; bf16x2v b = __builtin_convertvector(v, bf16x2v); return __builtin_bit_cast(unsigned, b); }
; DI float sigmoidf_(float x) { return 1.f / (1.f + __expf(-x)); }
; template <int TM, int WM, int WN, int TNSEL, class F>
; DI void stage_half(const f32x16 (&acc)[TM][2], char* tile, int pitch, F f) {
;     ...
;     char* d = tile + (wn * 32 + r) * pitch + (wm * TM * 32 + tm * 32 + 4 * hh) * 2;
; #pragma unroll
;     for (int q = 0; q < 4; ++q) {
;       const f32x16& a = acc[tm][TNSEL];
;       uint2 o; o.x = pk_bf16(f(a[4 * q]), f(a[4 * q + 1])); o.y = pk_bf16(f(a[4 * q + 2]), f(a[4 * q + 3]));
;       *(uint2*)(d + 16 * q) = o;
;     }
; DI void phase2(const Params& p, char* smem) {
;     ...
;     if (ft >= 5) stage_half<4, 2, 4, 0>(acc, tile, 528, [](float v) { return sigmoidf_(v); });
;     else stage_half<4, 2, 4, 0>(acc, tile, 528, [](float v) { return v; });
	v_mul_f32_e32 v108, 0xbfb8aa3b, v108
	v_mul_f32_e32 v109, 0xbfb8aa3b, v109
	v_mul_f32_e32 v110, 0xbfb8aa3b, v110
	v_mul_f32_e32 v111, 0xbfb8aa3b, v111
	v_exp_f32_e32 v104, v104
	v_exp_f32_e32 v105, v105
	v_exp_f32_e32 v106, v106
	v_exp_f32_e32 v107, v107
	v_exp_f32_e32 v108, v108
	v_exp_f32_e32 v109, v109
	v_exp_f32_e32 v110, v110
	v_exp_f32_e32 v111, v111
	v_add_f32_e32 v104, 1.0, v104
	v_add_f32_e32 v105, 1.0, v105
	v_add_f32_e32 v106, 1.0, v106
	v_add_f32_e32 v107, 1.0, v107
	v_add_f32_e32 v108, 1.0, v108
	v_add_f32_e32 v109, 1.0, v109
	v_add_f32_e32 v110, 1.0, v110
	v_add_f32_e32 v111, 1.0, v111
	v_rcp_f32_e32 v104, v104
	v_rcp_f32_e32 v105, v105
	v_rcp_f32_e32 v106, v106
	v_rcp_f32_e32 v107, v107
	v_rcp_f32_e32 v108, v108
	v_rcp_f32_e32 v109, v109
	v_rcp_f32_e32 v110, v110
	v_rcp_f32_e32 v111, v111
	v_mul_f32_e32 v112, 0xbfb8aa3b, v112
	v_mul_f32_e32 v113, 0xbfb8aa3b, v113
	v_mul_f32_e32 v114, 0xbfb8aa3b, v114
	v_mul_f32_e32 v115, 0xbfb8aa3b, v115
	v_mul_f32_e32 v116, 0xbfb8aa3b, v116
	v_mul_f32_e32 v117, 0xbfb8aa3b, v117
	v_mul_f32_e32 v118, 0xbfb8aa3b, v118
	v_mul_f32_e32 v119, 0xbfb8aa3b, v119
	v_exp_f32_e32 v112, v112
	v_exp_f32_e32 v113, v113
	v_exp_f32_e32 v114, v114
	v_exp_f32_e32 v115, v115
	v_exp_f32_e32 v116, v116
	v_exp_f32_e32 v117, v117
	v_exp_f32_e32 v118, v118
	v_exp_f32_e32 v119, v119
	v_add_f32_e32 v112, 1.0, v112
	v_add_f32_e32 v113, 1.0, v113
	v_add_f32_e32 v114, 1.0, v114
	v_add_f32_e32 v115, 1.0, v115
	v_add_f32_e32 v116, 1.0, v116
	v_add_f32_e32 v117, 1.0, v117
	v_add_f32_e32 v118, 1.0, v118
	v_add_f32_e32 v119, 1.0, v119
	v_rcp_f32_e32 v112, v112
	v_rcp_f32_e32 v113, v113
	v_rcp_f32_e32 v114, v114
	v_rcp_f32_e32 v115, v115
	v_rcp_f32_e32 v116, v116
	v_rcp_f32_e32 v117, v117
	v_rcp_f32_e32 v118, v118
	v_rcp_f32_e32 v119, v119
	v_mul_f32_e32 v120, 0xbfb8aa3b, v120
	v_mul_f32_e32 v121, 0xbfb8aa3b, v121
	v_mul_f32_e32 v122, 0xbfb8aa3b, v122
	v_mul_f32_e32 v123, 0xbfb8aa3b, v123
	v_mul_f32_e32 v124, 0xbfb8aa3b, v124
	v_mul_f32_e32 v125, 0xbfb8aa3b, v125
	v_mul_f32_e32 v126, 0xbfb8aa3b, v126
	v_mul_f32_e32 v127, 0xbfb8aa3b, v127
	v_exp_f32_e32 v120, v120
	v_exp_f32_e32 v121, v121
	v_exp_f32_e32 v122, v122
	v_exp_f32_e32 v123, v123
	v_exp_f32_e32 v124, v124
	v_exp_f32_e32 v125, v125
	v_exp_f32_e32 v126, v126
	v_exp_f32_e32 v127, v127
	v_add_f32_e32 v120, 1.0, v120
	v_add_f32_e32 v121, 1.0, v121
	v_add_f32_e32 v122, 1.0, v122
	v_add_f32_e32 v123, 1.0, v123
	v_add_f32_e32 v124, 1.0, v124
	v_add_f32_e32 v125, 1.0, v125
	v_add_f32_e32 v126, 1.0, v126
	v_add_f32_e32 v127, 1.0, v127
	v_rcp_f32_e32 v120, v120
	v_rcp_f32_e32 v121, v121
	v_rcp_f32_e32 v122, v122
	v_rcp_f32_e32 v123, v123
	v_rcp_f32_e32 v124, v124
	v_rcp_f32_e32 v125, v125
	v_rcp_f32_e32 v126, v126
	v_rcp_f32_e32 v127, v127
.Lp2_id0:
	v_mov_b32_e32 v128, v220
	v_cvt_pk_bf16_f32 v133, v70, v71
	v_ashrrev_i32_e32 v129, 6, v128
	v_lshrrev_b32_e32 v131, 31, v128
	v_add_u32_e32 v131, v129, v131
	v_and_b32_e32 v130, 31, v128
	v_and_b32_e32 v132, 0xfffffe, v131
	v_lshlrev_b32_e32 v131, 4, v131
	v_and_or_b32 v130, v131, s59, v130
	v_sub_u32_e32 v129, v129, v132
	v_mul_lo_u32 v130, v130, s60
	v_lshl_add_u32 v129, v129, 8, v130
	v_lshrrev_b32_e32 v128, 2, v128
	v_and_or_b32 v128, v128, 8, v129
	v_add_u32_e32 v134, 0x10000, v128
	v_cvt_pk_bf16_f32 v128, v112, v113
	v_cvt_pk_bf16_f32 v129, v114, v115
	v_cvt_pk_bf16_f32 v130, v116, v117
	v_cvt_pk_bf16_f32 v131, v118, v119
	s_waitcnt vmcnt(0)
	ds_write2_b64 v134, v[128:129], v[130:131] offset1:2
	v_cvt_pk_bf16_f32 v128, v120, v121
	v_cvt_pk_bf16_f32 v129, v122, v123
	v_cvt_pk_bf16_f32 v130, v124, v125
	v_cvt_pk_bf16_f32 v131, v126, v127
	ds_write2_b64 v134, v[128:129], v[130:131] offset0:4 offset1:6
	v_cvt_pk_bf16_f32 v128, v96, v97
	v_cvt_pk_bf16_f32 v129, v98, v99
	v_cvt_pk_bf16_f32 v130, v100, v101
	v_cvt_pk_bf16_f32 v131, v102, v103
	ds_write2_b64 v134, v[128:129], v[130:131] offset0:8 offset1:10
	v_cvt_pk_bf16_f32 v128, v104, v105
	v_cvt_pk_bf16_f32 v129, v106, v107
	v_cvt_pk_bf16_f32 v130, v108, v109
	v_cvt_pk_bf16_f32 v131, v110, v111
	ds_write2_b64 v134, v[128:129], v[130:131] offset0:12 offset1:14
	v_cvt_pk_bf16_f32 v128, v80, v81
	v_cvt_pk_bf16_f32 v129, v82, v83
	v_cvt_pk_bf16_f32 v130, v84, v85
	v_cvt_pk_bf16_f32 v131, v86, v87
	ds_write2_b64 v134, v[128:129], v[130:131] offset0:16 offset1:18
	v_cvt_pk_bf16_f32 v128, v88, v89
	v_cvt_pk_bf16_f32 v129, v90, v91
	v_cvt_pk_bf16_f32 v130, v92, v93
	v_cvt_pk_bf16_f32 v131, v94, v95
	ds_write2_b64 v134, v[128:129], v[130:131] offset0:20 offset1:22
	v_cvt_pk_bf16_f32 v130, v64, v65
	v_cvt_pk_bf16_f32 v131, v66, v67
	v_cvt_pk_bf16_f32 v132, v68, v69
	ds_write2_b64 v134, v[130:131], v[132:133] offset0:24 offset1:26
	v_cvt_pk_bf16_f32 v130, v72, v73
	v_cvt_pk_bf16_f32 v131, v74, v75
	v_add_u32_e32 v128, 0xc0, v134
	ds_write_b64 v134, v[130:131] offset:224
	s_mov_b64 s[4:5], 0

; DI void lds_sync() { wait_lgkm0(); bar_(); }
; DI float sigmoidf_(float x) { return 1.f / (1.f + __expf(-x)); }
; DI void phase2(const Params& p, char* smem) {
;     ...
;     lds_sync();
;     copy_tile(tile, 528, 128, 5, [&](int rl) { return base + (size_t)((rl >> 5) * 64 + (rl & 31)) * ld; }, c0, c1);
;     lds_sync();
;     if (ft >= 5) stage_half<4, 2, 4, 1>(acc, tile, 528, [](float v) { return sigmoidf_(v); });
.LBB0_287:
	s_or_b64 exec, exec, s[12:13]
	s_waitcnt lgkmcnt(0)
	s_mov_b64 s[4:5], -1
	s_and_b64 vcc, exec, s[10:11]
	s_barrier
	s_cbranch_vccnz .Lp2_id1
	v_mul_f32_e32 v0, 0xbfb8aa3b, v0
	v_mul_f32_e32 v1, 0xbfb8aa3b, v1
	v_mul_f32_e32 v2, 0xbfb8aa3b, v2
	v_mul_f32_e32 v3, 0xbfb8aa3b, v3
	v_mul_f32_e32 v4, 0xbfb8aa3b, v4
	v_mul_f32_e32 v5, 0xbfb8aa3b, v5
	v_mul_f32_e32 v6, 0xbfb8aa3b, v6
	v_mul_f32_e32 v7, 0xbfb8aa3b, v7
	v_exp_f32_e32 v0, v0
	v_exp_f32_e32 v1, v1
	v_exp_f32_e32 v2, v2
	v_exp_f32_e32 v3, v3
	v_exp_f32_e32 v4, v4
	v_exp_f32_e32 v5, v5
	v_exp_f32_e32 v6, v6
	v_exp_f32_e32 v7, v7
	v_add_f32_e32 v0, 1.0, v0
	v_add_f32_e32 v1, 1.0, v1
	v_add_f32_e32 v2, 1.0, v2
	v_add_f32_e32 v3, 1.0, v3
	v_add_f32_e32 v4, 1.0, v4
	v_add_f32_e32 v5, 1.0, v5
	v_add_f32_e32 v6, 1.0, v6
	v_add_f32_e32 v7, 1.0, v7
	v_rcp_f32_e32 v0, v0
	v_rcp_f32_e32 v1, v1
	v_rcp_f32_e32 v2, v2
	v_rcp_f32_e32 v3, v3
	v_rcp_f32_e32 v4, v4
	v_rcp_f32_e32 v5, v5
	v_rcp_f32_e32 v6, v6
	v_rcp_f32_e32 v7, v7
	v_mul_f32_e32 v8, 0xbfb8aa3b, v8
	v_mul_f32_e32 v9, 0xbfb8aa3b, v9
	v_mul_f32_e32 v10, 0xbfb8aa3b, v10
	v_mul_f32_e32 v11, 0xbfb8aa3b, v11
	v_mul_f32_e32 v12, 0xbfb8aa3b, v12
	v_mul_f32_e32 v13, 0xbfb8aa3b, v13
	v_mul_f32_e32 v14, 0xbfb8aa3b, v14
	v_mul_f32_e32 v15, 0xbfb8aa3b, v15
	v_exp_f32_e32 v8, v8
	v_exp_f32_e32 v9, v9
	v_exp_f32_e32 v10, v10
	v_exp_f32_e32 v11, v11
	v_exp_f32_e32 v12, v12
	v_exp_f32_e32 v13, v13
	v_exp_f32_e32 v14, v14
	v_exp_f32_e32 v15, v15
	v_add_f32_e32 v8, 1.0, v8
	v_add_f32_e32 v9, 1.0, v9
	v_add_f32_e32 v10, 1.0, v10
	v_add_f32_e32 v11, 1.0, v11
	v_add_f32_e32 v12, 1.0, v12
	v_add_f32_e32 v13, 1.0, v13
	v_add_f32_e32 v14, 1.0, v14
	v_add_f32_e32 v15, 1.0, v15
	v_rcp_f32_e32 v8, v8
	v_rcp_f32_e32 v9, v9
	v_rcp_f32_e32 v10, v10
	v_rcp_f32_e32 v11, v11
	v_rcp_f32_e32 v12, v12
	v_rcp_f32_e32 v13, v13
	v_rcp_f32_e32 v14, v14
	v_rcp_f32_e32 v15, v15
	v_mul_f32_e32 v16, 0xbfb8aa3b, v16
	v_mul_f32_e32 v17, 0xbfb8aa3b, v17
	v_mul_f32_e32 v18, 0xbfb8aa3b, v18
	v_mul_f32_e32 v19, 0xbfb8aa3b, v19
	v_mul_f32_e32 v20, 0xbfb8aa3b, v20
	v_mul_f32_e32 v21, 0xbfb8aa3b, v21
	v_mul_f32_e32 v22, 0xbfb8aa3b, v22
	v_mul_f32_e32 v23, 0xbfb8aa3b, v23
	v_exp_f32_e32 v16, v16
	v_exp_f32_e32 v17, v17
	v_exp_f32_e32 v18, v18
	v_exp_f32_e32 v19, v19
	v_exp_f32_e32 v20, v20
	v_exp_f32_e32 v21, v21
	v_exp_f32_e32 v22, v22
	v_exp_f32_e32 v23, v23
	v_add_f32_e32 v16, 1.0, v16
	v_add_f32_e32 v17, 1.0, v17
	v_add_f32_e32 v18, 1.0, v18
	v_add_f32_e32 v19, 1.0, v19
	v_add_f32_e32 v20, 1.0, v20
	v_add_f32_e32 v21, 1.0, v21
	v_add_f32_e32 v22, 1.0, v22
	v_add_f32_e32 v23, 1.0, v23
	v_rcp_f32_e32 v16, v16
	v_rcp_f32_e32 v17, v17
	v_rcp_f32_e32 v18, v18
	v_rcp_f32_e32 v19, v19
	v_rcp_f32_e32 v20, v20
	v_rcp_f32_e32 v21, v21
	v_rcp_f32_e32 v22, v22
	v_rcp_f32_e32 v23, v23
	v_mul_f32_e32 v24, 0xbfb8aa3b, v24
	v_mul_f32_e32 v25, 0xbfb8aa3b, v25
	v_mul_f32_e32 v26, 0xbfb8aa3b, v26
	v_mul_f32_e32 v27, 0xbfb8aa3b, v27
	v_mul_f32_e32 v28, 0xbfb8aa3b, v28
	v_mul_f32_e32 v29, 0xbfb8aa3b, v29
	v_mul_f32_e32 v30, 0xbfb8aa3b, v30
	v_mul_f32_e32 v31, 0xbfb8aa3b, v31
	v_exp_f32_e32 v24, v24
	v_exp_f32_e32 v25, v25
	v_exp_f32_e32 v26, v26
	v_exp_f32_e32 v27, v27
	v_exp_f32_e32 v28, v28
	v_exp_f32_e32 v29, v29
	v_exp_f32_e32 v30, v30
	v_exp_f32_e32 v31, v31
	v_add_f32_e32 v24, 1.0, v24
	v_add_f32_e32 v25, 1.0, v25
	v_add_f32_e32 v26, 1.0, v26
	v_add_f32_e32 v27, 1.0, v27
	v_add_f32_e32 v28, 1.0, v28
	v_add_f32_e32 v29, 1.0, v29
	v_add_f32_e32 v30, 1.0, v30
	v_add_f32_e32 v31, 1.0, v31
	v_rcp_f32_e32 v24, v24
	v_rcp_f32_e32 v25, v25
	v_rcp_f32_e32 v26, v26
	v_rcp_f32_e32 v27, v27
	v_rcp_f32_e32 v28, v28
	v_rcp_f32_e32 v29, v29
	v_rcp_f32_e32 v30, v30
	v_rcp_f32_e32 v31, v31
	v_mul_f32_e32 v32, 0xbfb8aa3b, v32
	v_mul_f32_e32 v33, 0xbfb8aa3b, v33
	v_mul_f32_e32 v34, 0xbfb8aa3b, v34
	v_mul_f32_e32 v35, 0xbfb8aa3b, v35
	v_mul_f32_e32 v36, 0xbfb8aa3b, v36
	v_mul_f32_e32 v37, 0xbfb8aa3b, v37
	v_mul_f32_e32 v38, 0xbfb8aa3b, v38
	v_mul_f32_e32 v39, 0xbfb8aa3b, v39
	v_exp_f32_e32 v32, v32
	v_exp_f32_e32 v33, v33
	v_exp_f32_e32 v34, v34
	v_exp_f32_e32 v35, v35
	v_exp_f32_e32 v36, v36
	v_exp_f32_e32 v37, v37
	v_exp_f32_e32 v38, v38
	v_exp_f32_e32 v39, v39
	v_add_f32_e32 v32, 1.0, v32
	v_add_f32_e32 v33, 1.0, v33
	v_add_f32_e32 v34, 1.0, v34
	v_add_f32_e32 v35, 1.0, v35
	v_add_f32_e32 v36, 1.0, v36
	v_add_f32_e32 v37, 1.0, v37
	v_add_f32_e32 v38, 1.0, v38
	v_add_f32_e32 v39, 1.0, v39
	v_rcp_f32_e32 v32, v32
	v_rcp_f32_e32 v33, v33
	v_rcp_f32_e32 v34, v34
	v_rcp_f32_e32 v35, v35
	v_rcp_f32_e32 v36, v36
	v_rcp_f32_e32 v37, v37
	v_rcp_f32_e32 v38, v38
	v_rcp_f32_e32 v39, v39
	v_mul_f32_e32 v40, 0xbfb8aa3b, v40
; DI unsigned pk_bf16(float lo, float hi) { f32x2v v = {lo, hi}; bf16x2v b = __builtin_convertvector(v, bf16x2v); return __builtin_bit_cast(unsigned, b); }
; DI float sigmoidf_(float x) { return 1.f / (1.f + __expf(-x)); }
; template <int TM, int WM, int WN, int TNSEL, class F>
; DI void stage_half(const f32x16 (&acc)[TM][2], char* tile, int pitch, F f) {
;     ...
;     char* d = tile + (wn * 32 + r) * pitch + (wm * TM * 32 + tm * 32 + 4 * hh) * 2;
; #pragma unroll
;     for (int q = 0; q < 4; ++q) {
;       const f32x16& a = acc[tm][TNSEL];
;       uint2 o; o.x = pk_bf16(f(a[4 * q]), f(a[4 * q + 1])); o.y = pk_bf16(f(a[4 * q + 2]), f(a[4 * q + 3]));
;       *(uint2*)(d + 16 * q) = o;
;     }
; DI void phase2(const Params& p, char* smem) {
;     ...
;     if (ft >= 5) stage_half<4, 2, 4, 1>(acc, tile, 528, [](float v) { return sigmoidf_(v); });
;     else stage_half<4, 2, 4, 1>(acc, tile, 528, [](float v) { return v; });
	v_mul_f32_e32 v41, 0xbfb8aa3b, v41
	v_mul_f32_e32 v42, 0xbfb8aa3b, v42
	v_mul_f32_e32 v43, 0xbfb8aa3b, v43
	v_mul_f32_e32 v44, 0xbfb8aa3b, v44
	v_mul_f32_e32 v45, 0xbfb8aa3b, v45
	v_mul_f32_e32 v46, 0xbfb8aa3b, v46
	v_mul_f32_e32 v47, 0xbfb8aa3b, v47
	v_exp_f32_e32 v40, v40
	v_exp_f32_e32 v41, v41
	v_exp_f32_e32 v42, v42
	v_exp_f32_e32 v43, v43
	v_exp_f32_e32 v44, v44
	v_exp_f32_e32 v45, v45
	v_exp_f32_e32 v46, v46
	v_exp_f32_e32 v47, v47
	v_add_f32_e32 v40, 1.0, v40
	v_add_f32_e32 v41, 1.0, v41
	v_add_f32_e32 v42, 1.0, v42
	v_add_f32_e32 v43, 1.0, v43
	v_add_f32_e32 v44, 1.0, v44
	v_add_f32_e32 v45, 1.0, v45
	v_add_f32_e32 v46, 1.0, v46
	v_add_f32_e32 v47, 1.0, v47
	v_rcp_f32_e32 v40, v40
	v_rcp_f32_e32 v41, v41
	v_rcp_f32_e32 v42, v42
	v_rcp_f32_e32 v43, v43
	v_rcp_f32_e32 v44, v44
	v_rcp_f32_e32 v45, v45
	v_rcp_f32_e32 v46, v46
	v_rcp_f32_e32 v47, v47
	v_mul_f32_e32 v48, 0xbfb8aa3b, v48
	v_mul_f32_e32 v49, 0xbfb8aa3b, v49
	v_mul_f32_e32 v50, 0xbfb8aa3b, v50
	v_mul_f32_e32 v51, 0xbfb8aa3b, v51
	v_mul_f32_e32 v52, 0xbfb8aa3b, v52
	v_mul_f32_e32 v53, 0xbfb8aa3b, v53
	v_mul_f32_e32 v54, 0xbfb8aa3b, v54
	v_mul_f32_e32 v55, 0xbfb8aa3b, v55
	v_exp_f32_e32 v48, v48
	v_exp_f32_e32 v49, v49
	v_exp_f32_e32 v50, v50
	v_exp_f32_e32 v51, v51
	v_exp_f32_e32 v52, v52
	v_exp_f32_e32 v53, v53
	v_exp_f32_e32 v54, v54
	v_exp_f32_e32 v55, v55
	v_add_f32_e32 v48, 1.0, v48
	v_add_f32_e32 v49, 1.0, v49
	v_add_f32_e32 v50, 1.0, v50
	v_add_f32_e32 v51, 1.0, v51
	v_add_f32_e32 v52, 1.0, v52
	v_add_f32_e32 v53, 1.0, v53
	v_add_f32_e32 v54, 1.0, v54
	v_add_f32_e32 v55, 1.0, v55
	v_rcp_f32_e32 v48, v48
	v_rcp_f32_e32 v49, v49
	v_rcp_f32_e32 v50, v50
	v_rcp_f32_e32 v51, v51
	v_rcp_f32_e32 v52, v52
	v_rcp_f32_e32 v53, v53
	v_rcp_f32_e32 v54, v54
	v_rcp_f32_e32 v55, v55
	v_mul_f32_e32 v56, 0xbfb8aa3b, v56
	v_mul_f32_e32 v57, 0xbfb8aa3b, v57
	v_mul_f32_e32 v58, 0xbfb8aa3b, v58
	v_mul_f32_e32 v59, 0xbfb8aa3b, v59
	v_mul_f32_e32 v60, 0xbfb8aa3b, v60
	v_mul_f32_e32 v61, 0xbfb8aa3b, v61
	v_mul_f32_e32 v62, 0xbfb8aa3b, v62
	v_mul_f32_e32 v63, 0xbfb8aa3b, v63
	v_exp_f32_e32 v56, v56
	v_exp_f32_e32 v57, v57
	v_exp_f32_e32 v58, v58
	v_exp_f32_e32 v59, v59
	v_exp_f32_e32 v60, v60
	v_exp_f32_e32 v61, v61
	v_exp_f32_e32 v62, v62
	v_exp_f32_e32 v63, v63
	v_add_f32_e32 v56, 1.0, v56
	v_add_f32_e32 v57, 1.0, v57
	v_add_f32_e32 v58, 1.0, v58
	v_add_f32_e32 v59, 1.0, v59
	v_add_f32_e32 v60, 1.0, v60
	v_add_f32_e32 v61, 1.0, v61
	v_add_f32_e32 v62, 1.0, v62
	v_add_f32_e32 v63, 1.0, v63
	v_rcp_f32_e32 v56, v56
	v_rcp_f32_e32 v57, v57
	v_rcp_f32_e32 v58, v58
	v_rcp_f32_e32 v59, v59
	v_rcp_f32_e32 v60, v60
	v_rcp_f32_e32 v61, v61
	v_rcp_f32_e32 v62, v62
	v_rcp_f32_e32 v63, v63
.Lp2_id1:
	v_mov_b32_e32 v64, v220
	v_cvt_pk_bf16_f32 v69, v6, v7
	v_ashrrev_i32_e32 v65, 6, v64
	v_lshrrev_b32_e32 v67, 31, v64
	v_add_u32_e32 v67, v65, v67
	v_and_b32_e32 v66, 31, v64
	v_and_b32_e32 v68, 0xfffffe, v67
	v_lshlrev_b32_e32 v67, 4, v67
	v_and_or_b32 v66, v67, s59, v66
	v_sub_u32_e32 v65, v65, v68
	v_mul_lo_u32 v66, v66, s60
	v_lshl_add_u32 v65, v65, 8, v66
	v_lshrrev_b32_e32 v64, 2, v64
	v_and_or_b32 v64, v64, 8, v65
	v_add_u32_e32 v70, 0x10000, v64
	v_cvt_pk_bf16_f32 v64, v48, v49
	v_cvt_pk_bf16_f32 v65, v50, v51
	v_cvt_pk_bf16_f32 v66, v52, v53
	v_cvt_pk_bf16_f32 v67, v54, v55
	ds_write2_b64 v70, v[64:65], v[66:67] offset1:2
	v_cvt_pk_bf16_f32 v64, v56, v57
	v_cvt_pk_bf16_f32 v65, v58, v59
	v_cvt_pk_bf16_f32 v66, v60, v61
	v_cvt_pk_bf16_f32 v67, v62, v63
	ds_write2_b64 v70, v[64:65], v[66:67] offset0:4 offset1:6
	v_cvt_pk_bf16_f32 v64, v32, v33
	v_cvt_pk_bf16_f32 v65, v34, v35
	v_cvt_pk_bf16_f32 v66, v36, v37
	v_cvt_pk_bf16_f32 v67, v38, v39
	ds_write2_b64 v70, v[64:65], v[66:67] offset0:8 offset1:10
	v_cvt_pk_bf16_f32 v64, v40, v41
	v_cvt_pk_bf16_f32 v65, v42, v43
	v_cvt_pk_bf16_f32 v66, v44, v45
	v_cvt_pk_bf16_f32 v67, v46, v47
	ds_write2_b64 v70, v[64:65], v[66:67] offset0:12 offset1:14
	v_cvt_pk_bf16_f32 v64, v16, v17
	v_cvt_pk_bf16_f32 v65, v18, v19
	v_cvt_pk_bf16_f32 v66, v20, v21
	v_cvt_pk_bf16_f32 v67, v22, v23
	ds_write2_b64 v70, v[64:65], v[66:67] offset0:16 offset1:18
	v_cvt_pk_bf16_f32 v64, v24, v25
	v_cvt_pk_bf16_f32 v65, v26, v27
	v_cvt_pk_bf16_f32 v66, v28, v29
	v_cvt_pk_bf16_f32 v67, v30, v31
	ds_write2_b64 v70, v[64:65], v[66:67] offset0:20 offset1:22
	v_cvt_pk_bf16_f32 v66, v0, v1
	v_cvt_pk_bf16_f32 v67, v2, v3
	v_cvt_pk_bf16_f32 v68, v4, v5
	ds_write2_b64 v70, v[66:67], v[68:69] offset0:24 offset1:26
	v_cvt_pk_bf16_f32 v66, v8, v9
	v_cvt_pk_bf16_f32 v67, v10, v11
	v_add_u32_e32 v64, 0xc0, v70
	ds_write_b64 v70, v[66:67] offset:224
	s_mov_b64 s[4:5], 0
